# baseline (speedup 1.0000x reference)
.LBB0_650:
	s_setprio 2
	v_readlane_b32 s40, v255, 15
	v_readlane_b32 s41, v255, 16
	s_load_dwordx2 s[14:15], s[40:41], 0xf0
	s_ashr_i32 s13, s12, 31
	s_lshl_b64 s[22:23], s[12:13], 20
	v_mov_b32_e32 v215, v1
	s_waitcnt lgkmcnt(0)
	s_add_u32 s2, s14, s22
	s_addc_u32 s13, s15, s23
	s_lshl_b32 s14, s39, 8
	s_ashr_i32 s15, s14, 31
	s_lshl_b64 s[24:25], s[14:15], 2
	s_add_u32 s22, s2, s24
	s_addc_u32 s23, s13, s25
	v_lshl_add_u64 v[130:131], s[22:23], 0, v[0:1]
	s_lshl_b32 s12, s12, 8
	v_lshl_add_u64 v[158:159], v[130:131], 0, v[214:215]
	s_ashr_i32 s13, s12, 31
	v_lshl_add_u64 v[130:131], v[158:159], 0, v[196:197]
	v_lshl_add_u64 v[160:161], s[12:13], 3, v[212:213]
	global_load_dwordx4 v[166:169], v[130:131], off
	global_load_dwordx4 v[154:157], v[130:131], off offset:64
	global_load_dwordx4 v[150:153], v[130:131], off offset:128
	global_load_dwordx4 v[146:149], v[130:131], off offset:192
	global_load_dwordx2 v[164:165], v[160:161], off
	global_load_dwordx2 v[162:163], v[160:161], off offset:128
	v_lshl_add_u64 v[130:131], v[158:159], 0, v[198:199]
	global_load_dwordx4 v[142:145], v[130:131], off
	global_load_dwordx4 v[138:141], v[130:131], off offset:64
	global_load_dwordx4 v[134:137], v[130:131], off offset:128
	s_nop 0
	global_load_dwordx4 v[130:133], v[130:131], off offset:192
	s_load_dwordx4 s[12:15], s[40:41], 0x10
	s_waitcnt lgkmcnt(0)
	s_add_u32 s2, s12, s31
	s_addc_u32 s13, s13, 0
	s_add_u32 s12, s2, s24
	s_addc_u32 s13, s13, s25
	s_add_u32 s2, s14, s31
	s_addc_u32 s15, s15, 0
	s_add_u32 s14, s2, s24
	s_addc_u32 s15, s15, s25
	v_and_b32_e32 v253, 63, v182
	v_lshrrev_b32_e32 v249, 6, v182
	v_lshl_add_u32 v250, v253, 2, v0
	global_load_dword v251, v250, s[12:13]
	global_load_dword v252, v250, s[14:15]
	v_lshlrev_b32_e32 v249, 9, v249
	v_add_u32_e32 v249, 0x10000, v249
	v_add_u32_e32 v248, v249, v214
	v_lshl_add_u32 v249, v253, 2, v249
	s_waitcnt vmcnt(0)
	ds_write_b32 v249, v251
	ds_write_b32 v249, v252 offset:256
	s_waitcnt lgkmcnt(0)
	ds_read_b128 v[170:173], v248
	ds_read_b128 v[174:177], v248 offset:256
	s_waitcnt lgkmcnt(0)
	v_sub_f32_e32 v167, v167, v164
	v_sub_f32_e32 v166, v166, v164
	v_sub_f32_e32 v169, v169, v164
	v_sub_f32_e32 v168, v168, v164
	v_pk_mul_f32 v[166:167], v[164:165], v[166:167] op_sel:[1,0]
	v_pk_mul_f32 v[168:169], v[164:165], v[168:169] op_sel:[1,0]
	v_mov_b32_e32 v217, v1
	v_sub_f32_e32 v157, v157, v164
	v_sub_f32_e32 v156, v156, v164
	v_sub_f32_e32 v155, v155, v164
	v_sub_f32_e32 v154, v154, v164
	v_pk_mul_f32 v[154:155], v[164:165], v[154:155] op_sel:[1,0]
	v_pk_mul_f32 v[156:157], v[164:165], v[156:157] op_sel:[1,0]
	v_sub_f32_e32 v153, v153, v164
	v_sub_f32_e32 v152, v152, v164
	v_sub_f32_e32 v151, v151, v164
	v_sub_f32_e32 v150, v150, v164
	v_pk_mul_f32 v[150:151], v[164:165], v[150:151] op_sel:[1,0]
	v_pk_mul_f32 v[152:153], v[164:165], v[152:153] op_sel:[1,0]
	v_pk_fma_f32 v[166:167], v[166:167], v[170:171], v[174:175]
	v_pk_fma_f32 v[168:169], v[168:169], v[172:173], v[176:177]
	v_pk_fma_f32 v[126:127], v[166:167], s[0:1], v[126:127] op_sel_hi:[1,0,1]
	v_lshl_add_u64 v[166:167], s[22:23], 0, v[196:197]
	v_pk_fma_f32 v[128:129], v[168:169], s[0:1], v[128:129] op_sel_hi:[1,0,1]
	v_lshl_add_u64 v[170:171], v[166:167], 0, v[216:217]
	global_store_dwordx4 v[170:171], v[126:129], off
	s_nop 0
	ds_read_b128 v[126:129], v248 offset:64
	ds_read_b128 v[166:169], v248 offset:320
	s_waitcnt lgkmcnt(0)
	v_pk_fma_f32 v[128:129], v[156:157], v[128:129], v[168:169]
	v_pk_fma_f32 v[126:127], v[154:155], v[126:127], v[166:167]
	v_pk_fma_f32 v[124:125], v[128:129], s[0:1], v[124:125] op_sel_hi:[1,0,1]
	v_pk_fma_f32 v[122:123], v[126:127], s[0:1], v[122:123] op_sel_hi:[1,0,1]
	global_store_dwordx4 v[170:171], v[122:125], off offset:64
	s_nop 0
	ds_read_b128 v[122:125], v248 offset:128
	ds_read_b128 v[126:129], v248 offset:384
	s_waitcnt lgkmcnt(0)
	v_pk_fma_f32 v[124:125], v[152:153], v[124:125], v[128:129]
	v_pk_fma_f32 v[122:123], v[150:151], v[122:123], v[126:127]
	v_pk_fma_f32 v[120:121], v[124:125], s[0:1], v[120:121] op_sel_hi:[1,0,1]
	v_pk_fma_f32 v[118:119], v[122:123], s[0:1], v[118:119] op_sel_hi:[1,0,1]
	global_store_dwordx4 v[170:171], v[118:121], off offset:128
	s_nop 0
	ds_read_b128 v[118:121], v248 offset:192
	ds_read_b128 v[122:125], v248 offset:448
	v_sub_f32_e32 v127, v149, v164
	v_sub_f32_e32 v126, v148, v164
	v_sub_f32_e32 v129, v147, v164
	v_sub_f32_e32 v128, v146, v164
	v_pk_mul_f32 v[128:129], v[164:165], v[128:129] op_sel:[1,0]
	v_pk_mul_f32 v[126:127], v[164:165], v[126:127] op_sel:[1,0]
	s_waitcnt lgkmcnt(0)
	v_pk_fma_f32 v[118:119], v[128:129], v[118:119], v[122:123]
	v_pk_fma_f32 v[120:121], v[126:127], v[120:121], v[124:125]
	v_pk_fma_f32 v[114:115], v[118:119], s[0:1], v[114:115] op_sel_hi:[1,0,1]
	v_pk_fma_f32 v[116:117], v[120:121], s[0:1], v[116:117] op_sel_hi:[1,0,1]
	global_store_dwordx4 v[170:171], v[114:117], off offset:192
	s_nop 0
	ds_read_b128 v[114:117], v248
	ds_read_b128 v[118:121], v248 offset:256
	v_sub_f32_e32 v125, v143, v162
	v_sub_f32_e32 v124, v142, v162
	v_sub_f32_e32 v123, v145, v162
	v_sub_f32_e32 v122, v144, v162
	v_pk_mul_f32 v[124:125], v[162:163], v[124:125] op_sel:[1,0]
	v_pk_mul_f32 v[122:123], v[162:163], v[122:123] op_sel:[1,0]
	s_waitcnt lgkmcnt(0)
	v_pk_fma_f32 v[114:115], v[124:125], v[114:115], v[118:119]
	v_pk_fma_f32 v[116:117], v[122:123], v[116:117], v[120:121]
	v_pk_fma_f32 v[110:111], v[114:115], s[0:1], v[110:111] op_sel_hi:[1,0,1]
	v_lshl_add_u64 v[114:115], s[22:23], 0, v[198:199]
	v_pk_fma_f32 v[112:113], v[116:117], s[0:1], v[112:113] op_sel_hi:[1,0,1]
	v_lshl_add_u64 v[118:119], v[114:115], 0, v[216:217]
	global_store_dwordx4 v[118:119], v[110:113], off
	s_nop 0
	ds_read_b128 v[110:113], v248 offset:64
	ds_read_b128 v[114:117], v248 offset:320
	v_sub_f32_e32 v121, v141, v162
	v_sub_f32_e32 v120, v140, v162
	v_sub_f32_e32 v123, v139, v162
	v_sub_f32_e32 v122, v138, v162
	v_pk_mul_f32 v[122:123], v[162:163], v[122:123] op_sel:[1,0]
	v_pk_mul_f32 v[120:121], v[162:163], v[120:121] op_sel:[1,0]
	s_waitcnt lgkmcnt(0)
	v_pk_fma_f32 v[110:111], v[122:123], v[110:111], v[114:115]
	v_pk_fma_f32 v[112:113], v[120:121], v[112:113], v[116:117]
	v_pk_fma_f32 v[106:107], v[110:111], s[0:1], v[106:107] op_sel_hi:[1,0,1]
	v_pk_fma_f32 v[108:109], v[112:113], s[0:1], v[108:109] op_sel_hi:[1,0,1]
	global_store_dwordx4 v[118:119], v[106:109], off offset:64
	s_nop 0
	ds_read_b128 v[106:109], v248 offset:128
	ds_read_b128 v[110:113], v248 offset:384
	v_sub_f32_e32 v115, v137, v162
	v_sub_f32_e32 v114, v136, v162
	v_sub_f32_e32 v117, v135, v162
	v_sub_f32_e32 v116, v134, v162
	v_pk_mul_f32 v[116:117], v[162:163], v[116:117] op_sel:[1,0]
	v_pk_mul_f32 v[114:115], v[162:163], v[114:115] op_sel:[1,0]
	s_waitcnt lgkmcnt(0)
	v_pk_fma_f32 v[106:107], v[116:117], v[106:107], v[110:111]
	v_pk_fma_f32 v[108:109], v[114:115], v[108:109], v[112:113]
	v_pk_fma_f32 v[102:103], v[106:107], s[0:1], v[102:103] op_sel_hi:[1,0,1]
	v_pk_fma_f32 v[104:105], v[108:109], s[0:1], v[104:105] op_sel_hi:[1,0,1]
	global_store_dwordx4 v[118:119], v[102:105], off offset:128
	s_nop 0
	ds_read_b128 v[102:105], v248 offset:192
	ds_read_b128 v[106:109], v248 offset:448
	v_sub_f32_e32 v111, v133, v162
	v_sub_f32_e32 v110, v132, v162
	v_sub_f32_e32 v113, v131, v162
	v_sub_f32_e32 v112, v130, v162
	v_pk_mul_f32 v[112:113], v[162:163], v[112:113] op_sel:[1,0]
	v_pk_mul_f32 v[110:111], v[162:163], v[110:111] op_sel:[1,0]
	s_waitcnt lgkmcnt(0)
	v_pk_fma_f32 v[102:103], v[112:113], v[102:103], v[106:107]
	v_pk_fma_f32 v[104:105], v[110:111], v[104:105], v[108:109]
	v_pk_fma_f32 v[98:99], v[102:103], s[0:1], v[98:99] op_sel_hi:[1,0,1]
	v_pk_fma_f32 v[100:101], v[104:105], s[0:1], v[100:101] op_sel_hi:[1,0,1]
	global_store_dwordx4 v[118:119], v[98:101], off offset:192
	s_nop 1
	v_lshl_add_u64 v[98:99], v[158:159], 0, v[200:201]
	global_load_dwordx4 v[112:115], v[98:99], off
	global_load_dwordx4 v[116:119], v[98:99], off offset:64
	global_load_dwordx4 v[120:123], v[98:99], off offset:128
	global_load_dwordx4 v[124:127], v[98:99], off offset:192
	global_load_dwordx2 v[140:141], v[160:161], off offset:256
	global_load_dwordx2 v[110:111], v[160:161], off offset:384
	v_lshl_add_u64 v[98:99], v[158:159], 0, v[202:203]
	global_load_dwordx4 v[128:131], v[98:99], off
	global_load_dwordx4 v[106:109], v[98:99], off offset:64
	global_load_dwordx4 v[102:105], v[98:99], off offset:128
	s_nop 0
	global_load_dwordx4 v[98:101], v[98:99], off offset:192
	s_nop 0
	ds_read_b128 v[132:135], v248
	ds_read_b128 v[136:139], v248 offset:256
	s_waitcnt vmcnt(5)
	v_sub_f32_e32 v113, v113, v140
	v_sub_f32_e32 v112, v112, v140
	v_sub_f32_e32 v115, v115, v140
	v_sub_f32_e32 v114, v114, v140
	v_pk_mul_f32 v[112:113], v[140:141], v[112:113] op_sel:[1,0]
	v_pk_mul_f32 v[114:115], v[140:141], v[114:115] op_sel:[1,0]
	v_sub_f32_e32 v119, v119, v140
	v_sub_f32_e32 v118, v118, v140
	v_sub_f32_e32 v117, v117, v140
	v_sub_f32_e32 v116, v116, v140
	v_pk_mul_f32 v[116:117], v[140:141], v[116:117] op_sel:[1,0]
	v_pk_mul_f32 v[118:119], v[140:141], v[118:119] op_sel:[1,0]
	s_waitcnt vmcnt(0) lgkmcnt(0)
	v_pk_fma_f32 v[112:113], v[112:113], v[132:133], v[136:137]
	v_pk_fma_f32 v[114:115], v[114:115], v[134:135], v[138:139]
	v_pk_fma_f32 v[94:95], v[112:113], s[0:1], v[94:95] op_sel_hi:[1,0,1]
	v_lshl_add_u64 v[112:113], s[22:23], 0, v[200:201]
	v_pk_fma_f32 v[96:97], v[114:115], s[0:1], v[96:97] op_sel_hi:[1,0,1]
	v_lshl_add_u64 v[132:133], v[112:113], 0, v[216:217]
	global_store_dwordx4 v[132:133], v[94:97], off
	s_nop 0
	ds_read_b128 v[94:97], v248 offset:64
	ds_read_b128 v[112:115], v248 offset:320
	s_waitcnt lgkmcnt(0)
	v_pk_fma_f32 v[96:97], v[118:119], v[96:97], v[114:115]
	v_pk_fma_f32 v[94:95], v[116:117], v[94:95], v[112:113]
	v_pk_fma_f32 v[92:93], v[96:97], s[0:1], v[92:93] op_sel_hi:[1,0,1]
	v_pk_fma_f32 v[90:91], v[94:95], s[0:1], v[90:91] op_sel_hi:[1,0,1]
	global_store_dwordx4 v[132:133], v[90:93], off offset:64
	s_nop 0
	ds_read_b128 v[90:93], v248 offset:128
	ds_read_b128 v[94:97], v248 offset:384
	v_sub_f32_e32 v113, v123, v140
	v_sub_f32_e32 v112, v122, v140
	v_sub_f32_e32 v115, v121, v140
	v_sub_f32_e32 v114, v120, v140
	v_pk_mul_f32 v[114:115], v[140:141], v[114:115] op_sel:[1,0]
	v_pk_mul_f32 v[112:113], v[140:141], v[112:113] op_sel:[1,0]
	s_waitcnt lgkmcnt(0)
	v_pk_fma_f32 v[90:91], v[114:115], v[90:91], v[94:95]
	v_pk_fma_f32 v[92:93], v[112:113], v[92:93], v[96:97]
	v_pk_fma_f32 v[86:87], v[90:91], s[0:1], v[86:87] op_sel_hi:[1,0,1]
	v_pk_fma_f32 v[88:89], v[92:93], s[0:1], v[88:89] op_sel_hi:[1,0,1]
	global_store_dwordx4 v[132:133], v[86:89], off offset:128
	s_nop 0
	ds_read_b128 v[86:89], v248 offset:192
	ds_read_b128 v[90:93], v248 offset:448
	v_sub_f32_e32 v95, v127, v140
	v_sub_f32_e32 v94, v126, v140
	v_sub_f32_e32 v97, v125, v140
	v_sub_f32_e32 v96, v124, v140
	v_pk_mul_f32 v[96:97], v[140:141], v[96:97] op_sel:[1,0]
	v_pk_mul_f32 v[94:95], v[140:141], v[94:95] op_sel:[1,0]
	s_waitcnt lgkmcnt(0)
	v_pk_fma_f32 v[86:87], v[96:97], v[86:87], v[90:91]
	v_pk_fma_f32 v[88:89], v[94:95], v[88:89], v[92:93]
	v_pk_fma_f32 v[82:83], v[86:87], s[0:1], v[82:83] op_sel_hi:[1,0,1]
	v_pk_fma_f32 v[84:85], v[88:89], s[0:1], v[84:85] op_sel_hi:[1,0,1]
	global_store_dwordx4 v[132:133], v[82:85], off offset:192
	s_nop 0
	ds_read_b128 v[82:85], v248
	ds_read_b128 v[86:89], v248 offset:256
	v_sub_f32_e32 v93, v129, v110
	v_sub_f32_e32 v92, v128, v110
	v_sub_f32_e32 v91, v131, v110
	v_sub_f32_e32 v90, v130, v110
	v_pk_mul_f32 v[92:93], v[110:111], v[92:93] op_sel:[1,0]
	v_pk_mul_f32 v[90:91], v[110:111], v[90:91] op_sel:[1,0]
	s_waitcnt lgkmcnt(0)
	v_pk_fma_f32 v[82:83], v[92:93], v[82:83], v[86:87]
	v_pk_fma_f32 v[84:85], v[90:91], v[84:85], v[88:89]
	v_pk_fma_f32 v[78:79], v[82:83], s[0:1], v[78:79] op_sel_hi:[1,0,1]
	v_lshl_add_u64 v[82:83], s[22:23], 0, v[202:203]
	v_pk_fma_f32 v[80:81], v[84:85], s[0:1], v[80:81] op_sel_hi:[1,0,1]
	v_lshl_add_u64 v[86:87], v[82:83], 0, v[216:217]
	global_store_dwordx4 v[86:87], v[78:81], off
	s_nop 0
	ds_read_b128 v[78:81], v248 offset:64
	ds_read_b128 v[82:85], v248 offset:320
	v_sub_f32_e32 v89, v109, v110
	v_sub_f32_e32 v88, v108, v110
	v_sub_f32_e32 v91, v107, v110
	v_sub_f32_e32 v90, v106, v110
	v_pk_mul_f32 v[90:91], v[110:111], v[90:91] op_sel:[1,0]
	v_pk_mul_f32 v[88:89], v[110:111], v[88:89] op_sel:[1,0]
	s_waitcnt lgkmcnt(0)
	v_pk_fma_f32 v[78:79], v[90:91], v[78:79], v[82:83]
	v_pk_fma_f32 v[80:81], v[88:89], v[80:81], v[84:85]
	v_pk_fma_f32 v[74:75], v[78:79], s[0:1], v[74:75] op_sel_hi:[1,0,1]
	v_pk_fma_f32 v[76:77], v[80:81], s[0:1], v[76:77] op_sel_hi:[1,0,1]
	global_store_dwordx4 v[86:87], v[74:77], off offset:64
	s_nop 0
	ds_read_b128 v[74:77], v248 offset:128
	ds_read_b128 v[78:81], v248 offset:384
	v_sub_f32_e32 v83, v105, v110
	v_sub_f32_e32 v82, v104, v110
	v_sub_f32_e32 v85, v103, v110
	v_sub_f32_e32 v84, v102, v110
	v_pk_mul_f32 v[84:85], v[110:111], v[84:85] op_sel:[1,0]
	v_pk_mul_f32 v[82:83], v[110:111], v[82:83] op_sel:[1,0]
	s_waitcnt lgkmcnt(0)
	v_pk_fma_f32 v[74:75], v[84:85], v[74:75], v[78:79]
	v_pk_fma_f32 v[76:77], v[82:83], v[76:77], v[80:81]
	v_pk_fma_f32 v[70:71], v[74:75], s[0:1], v[70:71] op_sel_hi:[1,0,1]
	v_pk_fma_f32 v[72:73], v[76:77], s[0:1], v[72:73] op_sel_hi:[1,0,1]
	global_store_dwordx4 v[86:87], v[70:73], off offset:128
	s_nop 0
	ds_read_b128 v[70:73], v248 offset:192
	ds_read_b128 v[74:77], v248 offset:448
	v_sub_f32_e32 v79, v101, v110
	v_sub_f32_e32 v78, v100, v110
	v_sub_f32_e32 v81, v99, v110
	v_sub_f32_e32 v80, v98, v110
	v_pk_mul_f32 v[80:81], v[110:111], v[80:81] op_sel:[1,0]
	v_pk_mul_f32 v[78:79], v[110:111], v[78:79] op_sel:[1,0]
	s_waitcnt lgkmcnt(0)
	v_pk_fma_f32 v[70:71], v[80:81], v[70:71], v[74:75]
	v_pk_fma_f32 v[72:73], v[78:79], v[72:73], v[76:77]
	v_pk_fma_f32 v[66:67], v[70:71], s[0:1], v[66:67] op_sel_hi:[1,0,1]
	v_pk_fma_f32 v[68:69], v[72:73], s[0:1], v[68:69] op_sel_hi:[1,0,1]
	global_store_dwordx4 v[86:87], v[66:69], off offset:192
	s_nop 1
	v_lshl_add_u64 v[66:67], v[158:159], 0, v[204:205]
	global_load_dwordx4 v[80:83], v[66:67], off
	global_load_dwordx4 v[84:87], v[66:67], off offset:64
	global_load_dwordx4 v[88:91], v[66:67], off offset:128
	global_load_dwordx4 v[92:95], v[66:67], off offset:192
	global_load_dwordx2 v[108:109], v[160:161], off offset:512
	global_load_dwordx2 v[78:79], v[160:161], off offset:640
	v_lshl_add_u64 v[66:67], v[158:159], 0, v[206:207]
	global_load_dwordx4 v[96:99], v[66:67], off
	global_load_dwordx4 v[74:77], v[66:67], off offset:64
	global_load_dwordx4 v[70:73], v[66:67], off offset:128
	s_nop 0
	global_load_dwordx4 v[66:69], v[66:67], off offset:192
	s_nop 0
	ds_read_b128 v[100:103], v248
	ds_read_b128 v[104:107], v248 offset:256
	s_waitcnt vmcnt(5)
	v_sub_f32_e32 v81, v81, v108
	v_sub_f32_e32 v80, v80, v108
	v_sub_f32_e32 v83, v83, v108
	v_sub_f32_e32 v82, v82, v108
	v_pk_mul_f32 v[80:81], v[108:109], v[80:81] op_sel:[1,0]
	v_pk_mul_f32 v[82:83], v[108:109], v[82:83] op_sel:[1,0]
	v_sub_f32_e32 v87, v87, v108
	v_sub_f32_e32 v86, v86, v108
	v_sub_f32_e32 v85, v85, v108
	v_sub_f32_e32 v84, v84, v108
	v_pk_mul_f32 v[84:85], v[108:109], v[84:85] op_sel:[1,0]
	v_pk_mul_f32 v[86:87], v[108:109], v[86:87] op_sel:[1,0]
	s_waitcnt vmcnt(0) lgkmcnt(0)
	v_pk_fma_f32 v[80:81], v[80:81], v[100:101], v[104:105]
	v_pk_fma_f32 v[82:83], v[82:83], v[102:103], v[106:107]
	v_pk_fma_f32 v[62:63], v[80:81], s[0:1], v[62:63] op_sel_hi:[1,0,1]
	v_lshl_add_u64 v[80:81], s[22:23], 0, v[204:205]
	v_pk_fma_f32 v[64:65], v[82:83], s[0:1], v[64:65] op_sel_hi:[1,0,1]
	v_lshl_add_u64 v[100:101], v[80:81], 0, v[216:217]
	global_store_dwordx4 v[100:101], v[62:65], off
	s_nop 0
	ds_read_b128 v[62:65], v248 offset:64
	ds_read_b128 v[80:83], v248 offset:320
	s_waitcnt lgkmcnt(0)
	v_pk_fma_f32 v[64:65], v[86:87], v[64:65], v[82:83]
	v_pk_fma_f32 v[62:63], v[84:85], v[62:63], v[80:81]
	v_pk_fma_f32 v[60:61], v[64:65], s[0:1], v[60:61] op_sel_hi:[1,0,1]
	v_pk_fma_f32 v[58:59], v[62:63], s[0:1], v[58:59] op_sel_hi:[1,0,1]
	global_store_dwordx4 v[100:101], v[58:61], off offset:64
	s_nop 0
	ds_read_b128 v[58:61], v248 offset:128
	ds_read_b128 v[62:65], v248 offset:384
	v_sub_f32_e32 v81, v91, v108
	v_sub_f32_e32 v80, v90, v108
	v_sub_f32_e32 v83, v89, v108
	v_sub_f32_e32 v82, v88, v108
	v_pk_mul_f32 v[82:83], v[108:109], v[82:83] op_sel:[1,0]
	v_pk_mul_f32 v[80:81], v[108:109], v[80:81] op_sel:[1,0]
	s_waitcnt lgkmcnt(0)
	v_pk_fma_f32 v[58:59], v[82:83], v[58:59], v[62:63]
	v_pk_fma_f32 v[60:61], v[80:81], v[60:61], v[64:65]
	v_pk_fma_f32 v[54:55], v[58:59], s[0:1], v[54:55] op_sel_hi:[1,0,1]
	v_pk_fma_f32 v[56:57], v[60:61], s[0:1], v[56:57] op_sel_hi:[1,0,1]
	global_store_dwordx4 v[100:101], v[54:57], off offset:128
	s_nop 0
	ds_read_b128 v[54:57], v248 offset:192
	ds_read_b128 v[58:61], v248 offset:448
	v_sub_f32_e32 v63, v95, v108
	v_sub_f32_e32 v62, v94, v108
	v_sub_f32_e32 v65, v93, v108
	v_sub_f32_e32 v64, v92, v108
	v_pk_mul_f32 v[64:65], v[108:109], v[64:65] op_sel:[1,0]
	v_pk_mul_f32 v[62:63], v[108:109], v[62:63] op_sel:[1,0]
	s_waitcnt lgkmcnt(0)
	v_pk_fma_f32 v[54:55], v[64:65], v[54:55], v[58:59]
	v_pk_fma_f32 v[56:57], v[62:63], v[56:57], v[60:61]
	v_pk_fma_f32 v[50:51], v[54:55], s[0:1], v[50:51] op_sel_hi:[1,0,1]
	v_pk_fma_f32 v[52:53], v[56:57], s[0:1], v[52:53] op_sel_hi:[1,0,1]
	global_store_dwordx4 v[100:101], v[50:53], off offset:192
	s_nop 0
	ds_read_b128 v[50:53], v248
	ds_read_b128 v[54:57], v248 offset:256
	v_sub_f32_e32 v61, v97, v78
	v_sub_f32_e32 v60, v96, v78
	v_sub_f32_e32 v59, v99, v78
	v_sub_f32_e32 v58, v98, v78
	v_pk_mul_f32 v[60:61], v[78:79], v[60:61] op_sel:[1,0]
	v_pk_mul_f32 v[58:59], v[78:79], v[58:59] op_sel:[1,0]
	s_waitcnt lgkmcnt(0)
	v_pk_fma_f32 v[50:51], v[60:61], v[50:51], v[54:55]
	v_pk_fma_f32 v[52:53], v[58:59], v[52:53], v[56:57]
	v_pk_fma_f32 v[46:47], v[50:51], s[0:1], v[46:47] op_sel_hi:[1,0,1]
	v_lshl_add_u64 v[50:51], s[22:23], 0, v[206:207]
	v_pk_fma_f32 v[48:49], v[52:53], s[0:1], v[48:49] op_sel_hi:[1,0,1]
	v_lshl_add_u64 v[54:55], v[50:51], 0, v[216:217]
	global_store_dwordx4 v[54:55], v[46:49], off
	s_nop 0
	ds_read_b128 v[46:49], v248 offset:64
	ds_read_b128 v[50:53], v248 offset:320
	v_sub_f32_e32 v57, v77, v78
	v_sub_f32_e32 v56, v76, v78
	v_sub_f32_e32 v59, v75, v78
	v_sub_f32_e32 v58, v74, v78
	v_pk_mul_f32 v[58:59], v[78:79], v[58:59] op_sel:[1,0]
	v_pk_mul_f32 v[56:57], v[78:79], v[56:57] op_sel:[1,0]
	s_waitcnt lgkmcnt(0)
	v_pk_fma_f32 v[46:47], v[58:59], v[46:47], v[50:51]
	v_pk_fma_f32 v[48:49], v[56:57], v[48:49], v[52:53]
	v_pk_fma_f32 v[42:43], v[46:47], s[0:1], v[42:43] op_sel_hi:[1,0,1]
	v_pk_fma_f32 v[44:45], v[48:49], s[0:1], v[44:45] op_sel_hi:[1,0,1]
	global_store_dwordx4 v[54:55], v[42:45], off offset:64
	s_nop 0
	ds_read_b128 v[42:45], v248 offset:128
	ds_read_b128 v[46:49], v248 offset:384
	v_sub_f32_e32 v51, v73, v78
	v_sub_f32_e32 v50, v72, v78
	v_sub_f32_e32 v53, v71, v78
	v_sub_f32_e32 v52, v70, v78
	v_pk_mul_f32 v[52:53], v[78:79], v[52:53] op_sel:[1,0]
	v_pk_mul_f32 v[50:51], v[78:79], v[50:51] op_sel:[1,0]
	s_waitcnt lgkmcnt(0)
	v_pk_fma_f32 v[42:43], v[52:53], v[42:43], v[46:47]
	v_pk_fma_f32 v[44:45], v[50:51], v[44:45], v[48:49]
	v_pk_fma_f32 v[38:39], v[42:43], s[0:1], v[38:39] op_sel_hi:[1,0,1]
	v_pk_fma_f32 v[40:41], v[44:45], s[0:1], v[40:41] op_sel_hi:[1,0,1]
	global_store_dwordx4 v[54:55], v[38:41], off offset:128
	s_nop 0
	ds_read_b128 v[38:41], v248 offset:192
	ds_read_b128 v[42:45], v248 offset:448
	v_sub_f32_e32 v47, v69, v78
	v_sub_f32_e32 v46, v68, v78
	v_sub_f32_e32 v49, v67, v78
	v_sub_f32_e32 v48, v66, v78
	v_pk_mul_f32 v[48:49], v[78:79], v[48:49] op_sel:[1,0]
	v_pk_mul_f32 v[46:47], v[78:79], v[46:47] op_sel:[1,0]
	s_waitcnt lgkmcnt(0)
	v_pk_fma_f32 v[38:39], v[48:49], v[38:39], v[42:43]
	v_pk_fma_f32 v[40:41], v[46:47], v[40:41], v[44:45]
	v_pk_fma_f32 v[34:35], v[38:39], s[0:1], v[34:35] op_sel_hi:[1,0,1]
	v_pk_fma_f32 v[36:37], v[40:41], s[0:1], v[36:37] op_sel_hi:[1,0,1]
	global_store_dwordx4 v[54:55], v[34:37], off offset:192
	s_nop 1
	v_lshl_add_u64 v[34:35], v[158:159], 0, v[208:209]
	global_load_dwordx4 v[48:51], v[34:35], off
	global_load_dwordx4 v[52:55], v[34:35], off offset:64
	global_load_dwordx4 v[56:59], v[34:35], off offset:128
	global_load_dwordx4 v[60:63], v[34:35], off offset:192
	global_load_dwordx2 v[76:77], v[160:161], off offset:768
	global_load_dwordx2 v[46:47], v[160:161], off offset:896
	v_lshl_add_u64 v[34:35], v[158:159], 0, v[210:211]
	global_load_dwordx4 v[64:67], v[34:35], off
	global_load_dwordx4 v[42:45], v[34:35], off offset:64
	global_load_dwordx4 v[38:41], v[34:35], off offset:128
	s_nop 0
	global_load_dwordx4 v[34:37], v[34:35], off offset:192
	s_nop 0
	ds_read_b128 v[68:71], v248
	ds_read_b128 v[72:75], v248 offset:256
	s_waitcnt vmcnt(5)
	v_sub_f32_e32 v49, v49, v76
	v_sub_f32_e32 v48, v48, v76
	v_sub_f32_e32 v51, v51, v76
	v_sub_f32_e32 v50, v50, v76
	v_pk_mul_f32 v[48:49], v[76:77], v[48:49] op_sel:[1,0]
	v_pk_mul_f32 v[50:51], v[76:77], v[50:51] op_sel:[1,0]
	v_sub_f32_e32 v55, v55, v76
	v_sub_f32_e32 v54, v54, v76
	v_sub_f32_e32 v53, v53, v76
	v_sub_f32_e32 v52, v52, v76
	v_pk_mul_f32 v[52:53], v[76:77], v[52:53] op_sel:[1,0]
	v_pk_mul_f32 v[54:55], v[76:77], v[54:55] op_sel:[1,0]
	s_waitcnt vmcnt(0) lgkmcnt(0)
	v_pk_fma_f32 v[48:49], v[48:49], v[68:69], v[72:73]
	v_pk_fma_f32 v[50:51], v[50:51], v[70:71], v[74:75]
	v_pk_fma_f32 v[30:31], v[48:49], s[0:1], v[30:31] op_sel_hi:[1,0,1]
	v_lshl_add_u64 v[48:49], s[22:23], 0, v[208:209]
	v_pk_fma_f32 v[32:33], v[50:51], s[0:1], v[32:33] op_sel_hi:[1,0,1]
	v_lshl_add_u64 v[68:69], v[48:49], 0, v[216:217]
	global_store_dwordx4 v[68:69], v[30:33], off
	s_nop 0
	ds_read_b128 v[30:33], v248 offset:64
	ds_read_b128 v[48:51], v248 offset:320
	s_waitcnt lgkmcnt(0)
; template <class DescFn, class EpiFn>
; __device__ __forceinline__ void gemm_phase(int nM, int nN, DescFn dfn, EpiFn efn) {
;     ...
;     efn(cpm, cpn)(acc, wr, wc, fr, fq);
;     if (!more) break;
	v_pk_fma_f32 v[32:33], v[54:55], v[32:33], v[50:51]
	v_pk_fma_f32 v[30:31], v[52:53], v[30:31], v[48:49]
	v_pk_fma_f32 v[28:29], v[32:33], s[0:1], v[28:29] op_sel_hi:[1,0,1]
	v_pk_fma_f32 v[26:27], v[30:31], s[0:1], v[26:27] op_sel_hi:[1,0,1]
	global_store_dwordx4 v[68:69], v[26:29], off offset:64
	s_nop 0
	ds_read_b128 v[26:29], v248 offset:128
	ds_read_b128 v[30:33], v248 offset:384
	v_sub_f32_e32 v49, v59, v76
	v_sub_f32_e32 v48, v58, v76
	v_sub_f32_e32 v51, v57, v76
	v_sub_f32_e32 v50, v56, v76
	v_pk_mul_f32 v[50:51], v[76:77], v[50:51] op_sel:[1,0]
	v_pk_mul_f32 v[48:49], v[76:77], v[48:49] op_sel:[1,0]
	s_waitcnt lgkmcnt(0)
	v_pk_fma_f32 v[26:27], v[50:51], v[26:27], v[30:31]
	v_pk_fma_f32 v[28:29], v[48:49], v[28:29], v[32:33]
	v_pk_fma_f32 v[22:23], v[26:27], s[0:1], v[22:23] op_sel_hi:[1,0,1]
	v_pk_fma_f32 v[24:25], v[28:29], s[0:1], v[24:25] op_sel_hi:[1,0,1]
	global_store_dwordx4 v[68:69], v[22:25], off offset:128
	s_nop 0
	ds_read_b128 v[22:25], v248 offset:192
	ds_read_b128 v[26:29], v248 offset:448
	v_sub_f32_e32 v31, v63, v76
	v_sub_f32_e32 v30, v62, v76
	v_sub_f32_e32 v33, v61, v76
	v_sub_f32_e32 v32, v60, v76
	v_pk_mul_f32 v[32:33], v[76:77], v[32:33] op_sel:[1,0]
	v_pk_mul_f32 v[30:31], v[76:77], v[30:31] op_sel:[1,0]
	s_waitcnt lgkmcnt(0)
	v_pk_fma_f32 v[22:23], v[32:33], v[22:23], v[26:27]
	v_pk_fma_f32 v[24:25], v[30:31], v[24:25], v[28:29]
	v_pk_fma_f32 v[18:19], v[22:23], s[0:1], v[18:19] op_sel_hi:[1,0,1]
	v_pk_fma_f32 v[20:21], v[24:25], s[0:1], v[20:21] op_sel_hi:[1,0,1]
	global_store_dwordx4 v[68:69], v[18:21], off offset:192
	s_nop 0
	ds_read_b128 v[18:21], v248
	ds_read_b128 v[22:25], v248 offset:256
	v_sub_f32_e32 v29, v65, v46
	v_sub_f32_e32 v28, v64, v46
	v_sub_f32_e32 v27, v67, v46
	v_sub_f32_e32 v26, v66, v46
	v_pk_mul_f32 v[28:29], v[46:47], v[28:29] op_sel:[1,0]
	v_pk_mul_f32 v[26:27], v[46:47], v[26:27] op_sel:[1,0]
	s_waitcnt lgkmcnt(0)
	v_pk_fma_f32 v[18:19], v[28:29], v[18:19], v[22:23]
	v_pk_fma_f32 v[20:21], v[26:27], v[20:21], v[24:25]
	v_pk_fma_f32 v[14:15], v[18:19], s[0:1], v[14:15] op_sel_hi:[1,0,1]
	v_lshl_add_u64 v[18:19], s[22:23], 0, v[210:211]
	v_pk_fma_f32 v[16:17], v[20:21], s[0:1], v[16:17] op_sel_hi:[1,0,1]
	v_lshl_add_u64 v[22:23], v[18:19], 0, v[216:217]
	global_store_dwordx4 v[22:23], v[14:17], off
	s_nop 0
	ds_read_b128 v[14:17], v248 offset:64
	ds_read_b128 v[18:21], v248 offset:320
	v_sub_f32_e32 v25, v45, v46
	v_sub_f32_e32 v24, v44, v46
	v_sub_f32_e32 v27, v43, v46
	v_sub_f32_e32 v26, v42, v46
	v_pk_mul_f32 v[26:27], v[46:47], v[26:27] op_sel:[1,0]
	v_pk_mul_f32 v[24:25], v[46:47], v[24:25] op_sel:[1,0]
	s_waitcnt lgkmcnt(0)
	v_pk_fma_f32 v[14:15], v[26:27], v[14:15], v[18:19]
	v_pk_fma_f32 v[16:17], v[24:25], v[16:17], v[20:21]
	v_pk_fma_f32 v[10:11], v[14:15], s[0:1], v[10:11] op_sel_hi:[1,0,1]
	v_pk_fma_f32 v[12:13], v[16:17], s[0:1], v[12:13] op_sel_hi:[1,0,1]
	global_store_dwordx4 v[22:23], v[10:13], off offset:64
	s_nop 0
	ds_read_b128 v[10:13], v248 offset:128
	ds_read_b128 v[14:17], v248 offset:384
	v_sub_f32_e32 v19, v41, v46
	v_sub_f32_e32 v18, v40, v46
	v_sub_f32_e32 v21, v39, v46
	v_sub_f32_e32 v20, v38, v46
	v_pk_mul_f32 v[20:21], v[46:47], v[20:21] op_sel:[1,0]
	v_pk_mul_f32 v[18:19], v[46:47], v[18:19] op_sel:[1,0]
	s_waitcnt lgkmcnt(0)
	v_pk_fma_f32 v[10:11], v[20:21], v[10:11], v[14:15]
	v_pk_fma_f32 v[12:13], v[18:19], v[12:13], v[16:17]
	v_pk_fma_f32 v[6:7], v[10:11], s[0:1], v[6:7] op_sel_hi:[1,0,1]
	v_pk_fma_f32 v[8:9], v[12:13], s[0:1], v[8:9] op_sel_hi:[1,0,1]
	global_store_dwordx4 v[22:23], v[6:9], off offset:128
	s_nop 0
	ds_read_b128 v[6:9], v248 offset:192
	ds_read_b128 v[10:13], v248 offset:448
	v_sub_f32_e32 v15, v37, v46
	v_sub_f32_e32 v14, v36, v46
	v_sub_f32_e32 v17, v35, v46
	v_sub_f32_e32 v16, v34, v46
	v_pk_mul_f32 v[16:17], v[46:47], v[16:17] op_sel:[1,0]
	v_pk_mul_f32 v[14:15], v[46:47], v[14:15] op_sel:[1,0]
	s_waitcnt lgkmcnt(0)
	v_pk_fma_f32 v[6:7], v[16:17], v[6:7], v[10:11]
	v_pk_fma_f32 v[8:9], v[14:15], v[8:9], v[12:13]
	v_pk_fma_f32 v[2:3], v[6:7], s[0:1], v[2:3] op_sel_hi:[1,0,1]
	v_pk_fma_f32 v[4:5], v[8:9], s[0:1], v[4:5] op_sel_hi:[1,0,1]
	global_store_dwordx4 v[22:23], v[2:5], off offset:192
	s_setprio 0
	s_andn2_b64 vcc, exec, s[20:21]
	s_mov_b64 s[12:13], -1
	s_cbranch_vccnz .LBB0_629
	s_mov_b64 s[12:13], 0
	s_branch .LBB0_629
